# remaining lane-half (xor 32) merges in the attention per-item code and the HGRN pass C norm reduction also via v_permlane32_swap instead of ds_bpermute
# baseline (speedup 1.0000x reference)
; #define LAS __attribute__((address_space(3)))
; DI unsigned pk2(float lo, float hi) { f32x2 v = {lo, hi}; bf2_t b = __builtin_convertvector(v, bf2_t); return __builtin_bit_cast(unsigned, b); }
; DI float fexp2(float x) { return __builtin_amdgcn_exp2f(x); }
; DI void attn_item(LAS unsigned char* lds, int bh, int qb, const bf16_t* QH, const bf16_t* KN, const bf16_t* KPE, const bf16_t* VT, const bf16_t* P, bf16_t* MIX) {
;     ...
;         float mx = S[0];
; #pragma unroll
;         for (int i = 1; i < 16; ++i) mx = fmaxf(mx, S[i]);
;         mx = fmaxf(mx, __shfl_xor(mx, 32));
;         if (__any(mx > mrow + 8.f)) {
;             const float mnew = fmaxf(mrow, mx);
;             const float alpha = fexp2(mrow - mnew);
;             mrow = mnew; lrow *= alpha;
; #pragma unroll
;             for (int d = 0; d < 4; ++d)
; #pragma unroll
;                 for (int i = 0; i < 16; ++i) O[d][i] *= alpha;
;         }
;         float ps = 0.f;
; #pragma unroll
;         for (int i = 0; i < 16; ++i) { float p = fexp2(S[i] - mrow); if (diag && S[i] == NEG) p = 0.f; S[i] = p; ps += p; }
;         lrow += ps;
;         bf16x8 pb[2];
; #pragma unroll
;         for (int s2 = 0; s2 < 2; ++s2) { u32x4 w; w.x = pk2(S[8 * s2 + 0], S[8 * s2 + 1]); w.y = pk2(S[8 * s2 + 2], S[8 * s2 + 3]); w.z = pk2(S[8 * s2 + 4], S[8 * s2 + 5]); w.w = pk2(S[8 * s2 + 6], S[8 * s2 + 7]); pb[s2] = __builtin_bit_cast(bf16x8, w); }
;         __builtin_amdgcn_s_setprio(1);
;         {
;             const int li = lane & 15, gd = (lane >> 4) & 1;
;             const LAS unsigned char* vp = vb + (kh * 32 + 4 * h2 + (li >> 2)) * VROW + gd * 32 + (li & 3) * 8;
; #pragma unroll
;             for (int d = 0; d < 4; ++d)
; #pragma unroll
;                 for (int s2 = 0; s2 < 2; ++s2) {
;                     const s16x4 lo = __builtin_amdgcn_ds_read_tr16_b64_v4i16((LAS s16x4*)(vp + (16 * s2) * VROW + 64 * d));
;                     const s16x4 hi = __builtin_amdgcn_ds_read_tr16_b64_v4i16((LAS s16x4*)(vp + (16 * s2 + 8) * VROW + 64 * d));
;                     const bf16x8 av = __builtin_shufflevector(lo, hi, 0, 1, 2, 3, 4, 5, 6, 7);
;                     O[d] = __builtin_amdgcn_mfma_f32_32x32x16_bf16(av, pb[s2], O[d], 0, 0, 0);
.LBB0_598:
	s_nop 6
	v_max_f32_e32 v128, v65, v65
	v_max_f32_e32 v129, v64, v64
	v_max_f32_e32 v128, v129, v128
	v_max3_f32 v128, v128, v66, v67
	v_max3_f32 v128, v128, v68, v69
	v_max3_f32 v128, v128, v70, v71
	v_max3_f32 v128, v128, v72, v73
	v_max3_f32 v128, v128, v74, v75
	v_max3_f32 v128, v128, v76, v77
	v_max3_f32 v128, v128, v78, v79
	v_mov_b32_e32 v129, v128
	s_nop 1
	v_permlane32_swap_b32_e32 v129, v128
	s_waitcnt lgkmcnt(0)
	v_max_f32_e32 v129, v129, v129
	v_max_f32_e32 v128, v128, v129
	v_add_f32_e32 v129, 0x41000000, v214
	v_cmp_gt_f32_e32 vcc, v128, v129
	s_cbranch_vccz .LBB0_600
	v_max_f32_e32 v128, v128, v128
	v_max_f32_e32 v129, v214, v214
	v_max_f32_e32 v130, v129, v128
	v_sub_f32_e32 v128, v214, v130
	v_exp_f32_e32 v128, v128
	v_mov_b32_e32 v214, v130
	v_pk_mul_f32 v[62:63], v[62:63], v[128:129] op_sel_hi:[1,0]
	v_pk_mul_f32 v[60:61], v[60:61], v[128:129] op_sel_hi:[1,0]
	v_pk_mul_f32 v[58:59], v[58:59], v[128:129] op_sel_hi:[1,0]
	v_pk_mul_f32 v[56:57], v[56:57], v[128:129] op_sel_hi:[1,0]
	v_pk_mul_f32 v[54:55], v[54:55], v[128:129] op_sel_hi:[1,0]
	v_pk_mul_f32 v[52:53], v[52:53], v[128:129] op_sel_hi:[1,0]
	v_pk_mul_f32 v[50:51], v[50:51], v[128:129] op_sel_hi:[1,0]
	v_pk_mul_f32 v[48:49], v[48:49], v[128:129] op_sel_hi:[1,0]
	v_pk_mul_f32 v[46:47], v[46:47], v[128:129] op_sel_hi:[1,0]
	v_pk_mul_f32 v[44:45], v[44:45], v[128:129] op_sel_hi:[1,0]
	v_pk_mul_f32 v[42:43], v[42:43], v[128:129] op_sel_hi:[1,0]
	v_pk_mul_f32 v[40:41], v[40:41], v[128:129] op_sel_hi:[1,0]
	v_pk_mul_f32 v[38:39], v[38:39], v[128:129] op_sel_hi:[1,0]
	v_pk_mul_f32 v[36:37], v[36:37], v[128:129] op_sel_hi:[1,0]
	v_pk_mul_f32 v[34:35], v[34:35], v[128:129] op_sel_hi:[1,0]
	v_pk_mul_f32 v[32:33], v[32:33], v[128:129] op_sel_hi:[1,0]
	v_pk_mul_f32 v[30:31], v[30:31], v[128:129] op_sel_hi:[1,0]
	v_pk_mul_f32 v[28:29], v[28:29], v[128:129] op_sel_hi:[1,0]
	v_pk_mul_f32 v[26:27], v[26:27], v[128:129] op_sel_hi:[1,0]
	v_pk_mul_f32 v[24:25], v[24:25], v[128:129] op_sel_hi:[1,0]
	v_pk_mul_f32 v[22:23], v[22:23], v[128:129] op_sel_hi:[1,0]
	v_pk_mul_f32 v[20:21], v[20:21], v[128:129] op_sel_hi:[1,0]
	v_pk_mul_f32 v[18:19], v[18:19], v[128:129] op_sel_hi:[1,0]
	v_pk_mul_f32 v[16:17], v[16:17], v[128:129] op_sel_hi:[1,0]
	v_pk_mul_f32 v[14:15], v[14:15], v[128:129] op_sel_hi:[1,0]
	v_pk_mul_f32 v[12:13], v[12:13], v[128:129] op_sel_hi:[1,0]
	v_pk_mul_f32 v[10:11], v[10:11], v[128:129] op_sel_hi:[1,0]
	v_pk_mul_f32 v[8:9], v[8:9], v[128:129] op_sel_hi:[1,0]
	v_pk_mul_f32 v[6:7], v[6:7], v[128:129] op_sel_hi:[1,0]
	v_pk_mul_f32 v[4:5], v[4:5], v[128:129] op_sel_hi:[1,0]
	v_pk_mul_f32 v[2:3], v[2:3], v[128:129] op_sel_hi:[1,0]
	v_pk_mul_f32 v[0:1], v[0:1], v[128:129] op_sel_hi:[1,0]
	v_mul_f32_e32 v234, v234, v128
	v_add_f32_e32 v129, 0x41000000, v130
.LBB0_600:
	v_sub_f32_e32 v128, v64, v214
	v_exp_f32_e32 v128, v128
	v_cmp_eq_f32_e32 vcc, s30, v64
	s_and_b64 s[42:43], s[22:23], vcc
	v_cmp_eq_f32_e32 vcc, s30, v65
	v_cndmask_b32_e64 v64, v128, 0, s[42:43]
	v_sub_f32_e32 v128, v65, v214
	v_exp_f32_e32 v128, v128
	s_and_b64 s[42:43], s[22:23], vcc
	v_cmp_eq_f32_e32 vcc, s30, v66
	v_add_f32_e32 v130, 0, v64
	v_cndmask_b32_e64 v65, v128, 0, s[42:43]
	v_sub_f32_e32 v128, v66, v214
	v_exp_f32_e32 v128, v128
	s_and_b64 s[42:43], s[22:23], vcc
	v_cmp_eq_f32_e32 vcc, s30, v67
	v_add_f32_e32 v130, v65, v130
	v_cndmask_b32_e64 v66, v128, 0, s[42:43]
	v_sub_f32_e32 v128, v67, v214
	v_exp_f32_e32 v128, v128
	s_and_b64 s[42:43], s[22:23], vcc
	v_cmp_eq_f32_e32 vcc, s30, v68
	v_add_f32_e32 v130, v66, v130
	v_cndmask_b32_e64 v67, v128, 0, s[42:43]
	v_sub_f32_e32 v128, v68, v214
	v_exp_f32_e32 v128, v128
	s_and_b64 s[42:43], s[22:23], vcc
	v_cmp_eq_f32_e32 vcc, s30, v69
	v_add_f32_e32 v130, v67, v130
	v_cndmask_b32_e64 v68, v128, 0, s[42:43]
	v_sub_f32_e32 v128, v69, v214
	v_exp_f32_e32 v128, v128
	s_and_b64 s[42:43], s[22:23], vcc
	v_cmp_eq_f32_e32 vcc, s30, v70
	v_add_f32_e32 v130, v68, v130
	v_cndmask_b32_e64 v69, v128, 0, s[42:43]
	v_sub_f32_e32 v128, v70, v214
	v_exp_f32_e32 v128, v128
	s_and_b64 s[42:43], s[22:23], vcc
	v_cmp_eq_f32_e32 vcc, s30, v71
	v_add_f32_e32 v130, v69, v130
	v_cndmask_b32_e64 v70, v128, 0, s[42:43]
	v_sub_f32_e32 v128, v71, v214
	v_exp_f32_e32 v128, v128
	s_and_b64 s[42:43], s[22:23], vcc
	v_cmp_eq_f32_e32 vcc, s30, v72
	v_add_f32_e32 v130, v70, v130
	v_cndmask_b32_e64 v71, v128, 0, s[42:43]
	v_sub_f32_e32 v128, v72, v214
	v_exp_f32_e32 v128, v128
	s_and_b64 s[42:43], s[22:23], vcc
	v_cmp_eq_f32_e32 vcc, s30, v73
	v_add_f32_e32 v130, v71, v130
	v_cndmask_b32_e64 v72, v128, 0, s[42:43]
	v_sub_f32_e32 v128, v73, v214
	v_exp_f32_e32 v128, v128
	s_and_b64 s[42:43], s[22:23], vcc
	v_cmp_eq_f32_e32 vcc, s30, v74
	v_add_f32_e32 v130, v72, v130
	v_cndmask_b32_e64 v73, v128, 0, s[42:43]
	v_sub_f32_e32 v128, v74, v214
	v_exp_f32_e32 v128, v128
	s_and_b64 s[42:43], s[22:23], vcc
	v_cmp_eq_f32_e32 vcc, s30, v75
	v_add_f32_e32 v130, v73, v130
	v_cndmask_b32_e64 v74, v128, 0, s[42:43]
	v_sub_f32_e32 v128, v75, v214
	v_exp_f32_e32 v128, v128
	s_and_b64 s[42:43], s[22:23], vcc
	v_cmp_eq_f32_e32 vcc, s30, v76
	v_add_f32_e32 v130, v74, v130
	v_cndmask_b32_e64 v75, v128, 0, s[42:43]
	v_sub_f32_e32 v128, v76, v214
	v_exp_f32_e32 v128, v128
	s_and_b64 s[42:43], s[22:23], vcc
	v_cmp_eq_f32_e32 vcc, s30, v77
	v_add_f32_e32 v130, v75, v130
	v_cndmask_b32_e64 v76, v128, 0, s[42:43]
	v_sub_f32_e32 v128, v77, v214
	v_exp_f32_e32 v128, v128
	s_and_b64 s[42:43], s[22:23], vcc
	v_cmp_eq_f32_e32 vcc, s30, v78
	v_add_f32_e32 v130, v76, v130
	v_cndmask_b32_e64 v77, v128, 0, s[42:43]
	v_sub_f32_e32 v128, v78, v214
	v_exp_f32_e32 v128, v128
	s_and_b64 s[42:43], s[22:23], vcc
	v_cmp_eq_f32_e32 vcc, s30, v79
	v_add_f32_e32 v130, v77, v130
	v_cndmask_b32_e64 v78, v128, 0, s[42:43]
	v_sub_f32_e32 v128, v79, v214
	v_exp_f32_e32 v128, v128
	s_and_b64 s[22:23], s[22:23], vcc
	v_add_f32_e32 v130, v78, v130
	v_cvt_pk_bf16_f32 v64, v64, v65
	v_cndmask_b32_e64 v79, v128, 0, s[22:23]
	v_add_f32_e32 v128, v79, v130
	v_cvt_pk_bf16_f32 v65, v66, v67
	v_cvt_pk_bf16_f32 v66, v68, v69
	v_cvt_pk_bf16_f32 v67, v70, v71
	v_cvt_pk_bf16_f32 v68, v72, v73
	v_cvt_pk_bf16_f32 v69, v74, v75
	v_cvt_pk_bf16_f32 v70, v76, v77
	v_cvt_pk_bf16_f32 v71, v78, v79
	s_add_i32 s41, s41, -1
	s_setprio 1
	v_add_u32_e32 v72, s40, v215
	v_add3_u32 v78, v72, v225, v226
	ds_read_b64_tr_b16 v[72:73], v78 offset:25600
	ds_read_b64_tr_b16 v[74:75], v78 offset:28160
	ds_read_b64_tr_b16 v[130:131], v78 offset:25664
	ds_read_b64_tr_b16 v[134:135], v78 offset:25728
	ds_read_b64_tr_b16 v[138:139], v78 offset:25792
	ds_read_b64_tr_b16 v[132:133], v78 offset:28224
	ds_read_b64_tr_b16 v[136:137], v78 offset:28288
	ds_read_b64_tr_b16 v[140:141], v78 offset:28352
	ds_read_b64_tr_b16 v[76:77], v78 offset:33280
	s_waitcnt lgkmcnt(7)
; #define LAS __attribute__((address_space(3)))
; DI float fexp2(float x) { return __builtin_amdgcn_exp2f(x); }
; DI void attn_item(LAS unsigned char* lds, int bh, int qb, const bf16_t* QH, const bf16_t* KN, const bf16_t* KPE, const bf16_t* VT, const bf16_t* P, bf16_t* MIX) {
;     ...
;         { const LAS unsigned char* kp = kb + (kh * 32 + r) * KROW + 16 * h2;
;           __builtin_amdgcn_s_setprio(1);
; #pragma unroll
;           for (int ks = 0; ks < 12; ++ks) { const bf16x8 a = *(const LAS bf16x8*)(kp + 32 * ks); S = __builtin_amdgcn_mfma_f32_32x32x16_bf16(a, Qf[ks], S, 0, 0, 0); }
;           __builtin_amdgcn_sched_group_barrier(0x100, 4, 0);
; #pragma unroll
;           for (int i = 0; i < 8; ++i) { __builtin_amdgcn_sched_group_barrier(0x008, 1, 0); __builtin_amdgcn_sched_group_barrier(0x100, 1, 0); }
;           __builtin_amdgcn_sched_group_barrier(0x008, 4, 0);
;           __builtin_amdgcn_s_setprio(0); }
;         const bool diag = (t >= 2 * qb);
;         if (diag) {
;             const int key0 = t * 64 + kh * 32 + 4 * h2;
; #pragma unroll
;             for (int i = 0; i < 16; ++i) { const int key = key0 + (i & 3) + 8 * (i >> 2); if (key > qpos) S[i] = NEG; }
;         }
;         float mx = S[0];
; #pragma unroll
;         for (int i = 1; i < 16; ++i) mx = fmaxf(mx, S[i]);
;         mx = fmaxf(mx, __shfl_xor(mx, 32));
;         if (__any(mx > mrow + 8.f)) {
;             const float mnew = fmaxf(mrow, mx);
;             const float alpha = fexp2(mrow - mnew);
;             mrow = mnew; lrow *= alpha;
; #pragma unroll
;             for (int d = 0; d < 4; ++d)
; #pragma unroll
;                 for (int i = 0; i < 16; ++i) O[d][i] *= alpha;
;         }
	v_mfma_f32_32x32x16_bf16 v[48:63], v[72:75], v[64:67], v[48:63]
	ds_read_b64_tr_b16 v[74:75], v78 offset:30720
	ds_read_b64_tr_b16 v[142:143], v78 offset:30784
	ds_read_b64_tr_b16 v[240:241], v78 offset:30848
	ds_read_b64_tr_b16 v[244:245], v78 offset:30912
	ds_read_b64_tr_b16 v[144:145], v78 offset:33344
	ds_read_b64_tr_b16 v[242:243], v78 offset:33408
	ds_read_b64_tr_b16 v[246:247], v78 offset:33472
	s_waitcnt lgkmcnt(10)
	v_mfma_f32_32x32x16_bf16 v[32:47], v[130:133], v[64:67], v[32:47]
	v_add_f32_e32 v128, v234, v128
	s_waitcnt lgkmcnt(9)
	v_mfma_f32_32x32x16_bf16 v[16:31], v[134:137], v[64:67], v[16:31]
	s_waitcnt lgkmcnt(8)
	v_mfma_f32_32x32x16_bf16 v[0:15], v[138:141], v[64:67], v[0:15]
	s_waitcnt lgkmcnt(6)
	v_mfma_f32_32x32x16_bf16 v[48:63], v[74:77], v[68:71], v[48:63]
	s_waitcnt lgkmcnt(2)
	v_mfma_f32_32x32x16_bf16 v[32:47], v[142:145], v[68:71], v[32:47]
	s_waitcnt lgkmcnt(1)
	v_mfma_f32_32x32x16_bf16 v[16:31], v[240:243], v[68:71], v[16:31]
	s_waitcnt lgkmcnt(0)
	v_mfma_f32_32x32x16_bf16 v[0:15], v[244:247], v[68:71], v[0:15]
	s_setprio 0
	s_barrier
	v_add3_u32 v142, s39, v233, v164
	s_setprio 1
	ds_read_b128 v[64:67], v142
	ds_read_b128 v[130:133], v142 offset:32
	ds_read_b128 v[134:137], v142 offset:64
	ds_read_b128 v[138:141], v142 offset:96
	s_waitcnt lgkmcnt(3)
	v_mfma_f32_32x32x16_bf16 v[64:79], v[64:67], v[124:127], 0
	ds_read_b128 v[124:127], v142 offset:128
	s_waitcnt lgkmcnt(3)
	v_mfma_f32_32x32x16_bf16 v[64:79], v[130:133], v[120:123], v[64:79]
	ds_read_b128 v[120:123], v142 offset:160
	s_waitcnt lgkmcnt(3)
	v_mfma_f32_32x32x16_bf16 v[64:79], v[134:137], v[116:119], v[64:79]
	ds_read_b128 v[116:119], v142 offset:192
	s_waitcnt lgkmcnt(3)
	v_mfma_f32_32x32x16_bf16 v[64:79], v[138:141], v[112:115], v[64:79]
	ds_read_b128 v[112:115], v142 offset:224
	s_waitcnt lgkmcnt(3)
	v_mfma_f32_32x32x16_bf16 v[64:79], v[124:127], v[108:111], v[64:79]
	ds_read_b128 v[108:111], v142 offset:256
	s_waitcnt lgkmcnt(3)
	v_mfma_f32_32x32x16_bf16 v[64:79], v[120:123], v[104:107], v[64:79]
	ds_read_b128 v[104:107], v142 offset:288
	s_waitcnt lgkmcnt(3)
	v_mfma_f32_32x32x16_bf16 v[64:79], v[116:119], v[100:103], v[64:79]
	ds_read_b128 v[100:103], v142 offset:320
	s_waitcnt lgkmcnt(3)
	v_mfma_f32_32x32x16_bf16 v[64:79], v[112:115], v[96:99], v[64:79]
	ds_read_b128 v[96:99], v142 offset:352
	s_waitcnt lgkmcnt(3)
	v_mfma_f32_32x32x16_bf16 v[64:79], v[108:111], v[84:87], v[64:79]
	s_waitcnt lgkmcnt(2)
	v_mfma_f32_32x32x16_bf16 v[64:79], v[104:107], v[88:91], v[64:79]
	s_waitcnt lgkmcnt(1)
	v_mfma_f32_32x32x16_bf16 v[64:79], v[100:103], v[92:95], v[64:79]
	s_waitcnt lgkmcnt(0)
	v_mfma_f32_32x32x16_bf16 v[64:79], v[96:99], v[80:83], v[64:79]
	s_setprio 0
	s_lshl_b32 s22, s41, 6
	s_addk_i32 s22, 0x80
	v_add_u32_e32 v88, s22, v217
	v_cmp_le_u32_e32 vcc, v88, v216
	s_nop 6
	v_cndmask_b32_e32 v87, v230, v64, vcc
	v_cmp_lt_u32_e32 vcc, v88, v216
	v_or_b32_e32 v64, 2, v88
	s_nop 0
	v_cndmask_b32_e32 v86, v230, v65, vcc
	v_cmp_le_u32_e32 vcc, v64, v216
	v_or_b32_e32 v64, 3, v88
	v_or_b32_e32 v65, 27, v88
	v_cndmask_b32_e32 v84, v230, v66, vcc
	v_cmp_le_u32_e32 vcc, v64, v216
	v_or_b32_e32 v64, 8, v88
	s_nop 0
	v_cndmask_b32_e32 v85, v230, v67, vcc
	v_cmp_le_u32_e32 vcc, v64, v216
	v_or_b32_e32 v64, 9, v88
	s_nop 0
	v_cndmask_b32_e32 v82, v230, v68, vcc
	v_cmp_le_u32_e32 vcc, v64, v216
	v_or_b32_e32 v64, 10, v88
	s_nop 0
	v_cndmask_b32_e32 v83, v230, v69, vcc
	v_cmp_le_u32_e32 vcc, v64, v216
	v_or_b32_e32 v64, 11, v88
	s_nop 0
	v_cndmask_b32_e32 v80, v230, v70, vcc
	v_cmp_le_u32_e32 vcc, v64, v216
	v_or_b32_e32 v64, 16, v88
	s_nop 0
	v_cndmask_b32_e32 v81, v230, v71, vcc
	v_cmp_le_u32_e32 vcc, v64, v216
	v_or_b32_e32 v64, 17, v88
	s_nop 0
	v_cndmask_b32_e32 v70, v230, v72, vcc
	v_cmp_le_u32_e32 vcc, v64, v216
	v_or_b32_e32 v64, 18, v88
	v_max_f32_e32 v72, v86, v86
	v_cndmask_b32_e32 v71, v230, v73, vcc
	v_max_f32_e32 v73, v87, v87
	v_cmp_le_u32_e32 vcc, v64, v216
	v_or_b32_e32 v64, 19, v88
	v_max_f32_e32 v72, v73, v72
	v_cndmask_b32_e32 v68, v230, v74, vcc
	v_cmp_le_u32_e32 vcc, v64, v216
	v_or_b32_e32 v64, 24, v88
	v_max3_f32 v72, v72, v84, v85
	v_cndmask_b32_e32 v69, v230, v75, vcc
	v_cmp_le_u32_e32 vcc, v64, v216
	v_or_b32_e32 v64, 25, v88
	v_max3_f32 v72, v72, v82, v83
	v_cndmask_b32_e32 v66, v230, v76, vcc
	v_cmp_le_u32_e32 vcc, v64, v216
	v_or_b32_e32 v64, 26, v88
	v_max3_f32 v72, v72, v80, v81
	v_cndmask_b32_e32 v67, v230, v77, vcc
	v_cmp_le_u32_e32 vcc, v64, v216
	v_max3_f32 v72, v72, v70, v71
	v_max3_f32 v72, v72, v68, v69
	v_cndmask_b32_e32 v64, v230, v78, vcc
	v_cmp_le_u32_e32 vcc, v65, v216
	v_max3_f32 v72, v72, v66, v67
	s_nop 0
	v_cndmask_b32_e32 v65, v230, v79, vcc
	v_max3_f32 v72, v72, v64, v65
	v_mov_b32_e32 v73, v72
	s_nop 1
	v_permlane32_swap_b32_e32 v73, v72
	s_waitcnt lgkmcnt(0)
	v_max_f32_e32 v73, v73, v73
	v_max_f32_e32 v72, v72, v73
	v_cmp_gt_f32_e32 vcc, v72, v129
	s_cbranch_vccz .LBB0_602
	v_max_f32_e32 v72, v72, v72
	v_max_f32_e32 v73, v214, v214
	v_max_f32_e32 v73, v73, v72
	v_sub_f32_e32 v72, v214, v73
	v_exp_f32_e32 v72, v72
	v_mov_b32_e32 v214, v73
	v_pk_mul_f32 v[62:63], v[62:63], v[72:73] op_sel_hi:[1,0]
	v_pk_mul_f32 v[60:61], v[60:61], v[72:73] op_sel_hi:[1,0]
	v_pk_mul_f32 v[58:59], v[58:59], v[72:73] op_sel_hi:[1,0]
	v_pk_mul_f32 v[56:57], v[56:57], v[72:73] op_sel_hi:[1,0]
	v_pk_mul_f32 v[54:55], v[54:55], v[72:73] op_sel_hi:[1,0]
	v_pk_mul_f32 v[52:53], v[52:53], v[72:73] op_sel_hi:[1,0]
	v_pk_mul_f32 v[50:51], v[50:51], v[72:73] op_sel_hi:[1,0]
	v_pk_mul_f32 v[48:49], v[48:49], v[72:73] op_sel_hi:[1,0]
	v_pk_mul_f32 v[46:47], v[46:47], v[72:73] op_sel_hi:[1,0]
	v_pk_mul_f32 v[44:45], v[44:45], v[72:73] op_sel_hi:[1,0]
	v_pk_mul_f32 v[42:43], v[42:43], v[72:73] op_sel_hi:[1,0]
	v_pk_mul_f32 v[40:41], v[40:41], v[72:73] op_sel_hi:[1,0]
	v_pk_mul_f32 v[38:39], v[38:39], v[72:73] op_sel_hi:[1,0]
	v_pk_mul_f32 v[36:37], v[36:37], v[72:73] op_sel_hi:[1,0]
	v_pk_mul_f32 v[34:35], v[34:35], v[72:73] op_sel_hi:[1,0]
	v_pk_mul_f32 v[32:33], v[32:33], v[72:73] op_sel_hi:[1,0]
	v_pk_mul_f32 v[30:31], v[30:31], v[72:73] op_sel_hi:[1,0]
	v_pk_mul_f32 v[28:29], v[28:29], v[72:73] op_sel_hi:[1,0]
	v_pk_mul_f32 v[26:27], v[26:27], v[72:73] op_sel_hi:[1,0]
	v_pk_mul_f32 v[24:25], v[24:25], v[72:73] op_sel_hi:[1,0]
	v_pk_mul_f32 v[22:23], v[22:23], v[72:73] op_sel_hi:[1,0]
	v_pk_mul_f32 v[20:21], v[20:21], v[72:73] op_sel_hi:[1,0]
	v_pk_mul_f32 v[18:19], v[18:19], v[72:73] op_sel_hi:[1,0]
	v_pk_mul_f32 v[16:17], v[16:17], v[72:73] op_sel_hi:[1,0]
	v_pk_mul_f32 v[14:15], v[14:15], v[72:73] op_sel_hi:[1,0]
	v_pk_mul_f32 v[12:13], v[12:13], v[72:73] op_sel_hi:[1,0]
	v_pk_mul_f32 v[10:11], v[10:11], v[72:73] op_sel_hi:[1,0]
	v_pk_mul_f32 v[8:9], v[8:9], v[72:73] op_sel_hi:[1,0]
	v_pk_mul_f32 v[6:7], v[6:7], v[72:73] op_sel_hi:[1,0]
	v_pk_mul_f32 v[4:5], v[4:5], v[72:73] op_sel_hi:[1,0]
	v_pk_mul_f32 v[2:3], v[2:3], v[72:73] op_sel_hi:[1,0]
	v_pk_mul_f32 v[0:1], v[0:1], v[72:73] op_sel_hi:[1,0]
	v_mul_f32_e32 v128, v128, v72
; #define LAS __attribute__((address_space(3)))
; DI unsigned pk2(float lo, float hi) { f32x2 v = {lo, hi}; bf2_t b = __builtin_convertvector(v, bf2_t); return __builtin_bit_cast(unsigned, b); }
; DI float fexp2(float x) { return __builtin_amdgcn_exp2f(x); }
; DI void attn_item(LAS unsigned char* lds, int bh, int qb, const bf16_t* QH, const bf16_t* KN, const bf16_t* KPE, const bf16_t* VT, const bf16_t* P, bf16_t* MIX) {
;     ...
;         float ps = 0.f;
; #pragma unroll
;         for (int i = 0; i < 16; ++i) { float p = fexp2(S[i] - mrow); if (diag && S[i] == NEG) p = 0.f; S[i] = p; ps += p; }
;         lrow += ps;
;         bf16x8 pb[2];
; #pragma unroll
;         for (int s2 = 0; s2 < 2; ++s2) { u32x4 w; w.x = pk2(S[8 * s2 + 0], S[8 * s2 + 1]); w.y = pk2(S[8 * s2 + 2], S[8 * s2 + 3]); w.z = pk2(S[8 * s2 + 4], S[8 * s2 + 5]); w.w = pk2(S[8 * s2 + 6], S[8 * s2 + 7]); pb[s2] = __builtin_bit_cast(bf16x8, w); }
;         __builtin_amdgcn_s_setprio(1);
;         {
;             const int li = lane & 15, gd = (lane >> 4) & 1;
;             const LAS unsigned char* vp = vb + (kh * 32 + 4 * h2 + (li >> 2)) * VROW + gd * 32 + (li & 3) * 8;
; #pragma unroll
;             for (int d = 0; d < 4; ++d)
; #pragma unroll
;                 for (int s2 = 0; s2 < 2; ++s2) {
;                     const s16x4 lo = __builtin_amdgcn_ds_read_tr16_b64_v4i16((LAS s16x4*)(vp + (16 * s2) * VROW + 64 * d));
;                     const s16x4 hi = __builtin_amdgcn_ds_read_tr16_b64_v4i16((LAS s16x4*)(vp + (16 * s2 + 8) * VROW + 64 * d));
;                     const bf16x8 av = __builtin_shufflevector(lo, hi, 0, 1, 2, 3, 4, 5, 6, 7);
;                     O[d] = __builtin_amdgcn_mfma_f32_32x32x16_bf16(av, pb[s2], O[d], 0, 0, 0);
;                 }
;         }
;         __builtin_amdgcn_s_setprio(0);
;     }
;     __syncthreads();
;     ...
;     lrow += __shfl_xor(lrow, 32);
;     LAS float* mb = (LAS float*)lds + (rg * 64 + lane) * 66;
;     if (kh == 1) {
; #pragma unroll
;         for (int d = 0; d < 4; ++d)
; #pragma unroll
;             for (int i = 0; i < 16; ++i) mb[d * 16 + i] = O[d][i];
;         mb[64] = mrow; mb[65] = lrow;
.LBB0_602:
	v_sub_f32_e32 v72, v87, v214
	v_exp_f32_e32 v72, v72
	v_sub_f32_e32 v73, v86, v214
	v_exp_f32_e32 v73, v73
	v_sub_f32_e32 v75, v84, v214
	v_exp_f32_e32 v75, v75
	v_sub_f32_e32 v76, v85, v214
	v_cmp_neq_f32_e32 vcc, s30, v87
	v_exp_f32_e32 v76, v76
	v_sub_f32_e32 v77, v82, v214
	v_cndmask_b32_e32 v72, 0, v72, vcc
	v_cmp_neq_f32_e32 vcc, s30, v86
	v_exp_f32_e32 v77, v77
	v_sub_f32_e32 v78, v83, v214
	v_cndmask_b32_e32 v73, 0, v73, vcc
	v_cmp_neq_f32_e32 vcc, s30, v84
	v_exp_f32_e32 v78, v78
	v_sub_f32_e32 v79, v80, v214
	v_cndmask_b32_e32 v75, 0, v75, vcc
	v_cmp_neq_f32_e32 vcc, s30, v85
	v_exp_f32_e32 v79, v79
	v_add_f32_e32 v74, 0, v72
	v_cndmask_b32_e32 v76, 0, v76, vcc
	v_cmp_neq_f32_e32 vcc, s30, v82
	v_sub_f32_e32 v82, v81, v214
	v_exp_f32_e32 v82, v82
	v_cndmask_b32_e32 v77, 0, v77, vcc
	v_cmp_neq_f32_e32 vcc, s30, v83
	v_add_f32_e32 v74, v73, v74
	v_add_f32_e32 v74, v75, v74
	v_cndmask_b32_e32 v78, 0, v78, vcc
	v_cmp_neq_f32_e32 vcc, s30, v80
	v_add_f32_e32 v74, v76, v74
	v_add_f32_e32 v74, v77, v74
	v_cndmask_b32_e32 v79, 0, v79, vcc
	v_cmp_neq_f32_e32 vcc, s30, v81
	v_sub_f32_e32 v81, v70, v214
	v_exp_f32_e32 v81, v81
	v_cndmask_b32_e32 v80, 0, v82, vcc
	v_sub_f32_e32 v82, v71, v214
	v_cmp_neq_f32_e32 vcc, s30, v70
	v_exp_f32_e32 v82, v82
	v_add_f32_e32 v74, v78, v74
	v_cndmask_b32_e32 v70, 0, v81, vcc
	v_sub_f32_e32 v81, v68, v214
	v_exp_f32_e32 v81, v81
	v_add_f32_e32 v74, v79, v74
	v_add_f32_e32 v74, v80, v74
	v_cmp_neq_f32_e32 vcc, s30, v71
	v_add_f32_e32 v74, v70, v74
	s_nop 0
	v_cndmask_b32_e32 v71, 0, v82, vcc
	v_cmp_neq_f32_e32 vcc, s30, v68
	v_add_f32_e32 v74, v71, v74
	v_sub_f32_e32 v82, v69, v214
	v_cndmask_b32_e32 v81, 0, v81, vcc
	v_exp_f32_e32 v82, v82
	v_add_f32_e32 v68, v81, v74
	v_sub_f32_e32 v74, v66, v214
	v_exp_f32_e32 v74, v74
	v_cmp_neq_f32_e32 vcc, s30, v69
	s_nop 1
	v_cndmask_b32_e32 v69, 0, v82, vcc
	v_sub_f32_e32 v82, v67, v214
	v_cmp_neq_f32_e32 vcc, s30, v66
	v_add_f32_e32 v68, v69, v68
	v_exp_f32_e32 v82, v82
	v_cndmask_b32_e32 v74, 0, v74, vcc
	v_cmp_neq_f32_e32 vcc, s30, v67
	v_sub_f32_e32 v67, v64, v214
	v_add_f32_e32 v66, v74, v68
	v_exp_f32_e32 v67, v67
	v_sub_f32_e32 v68, v65, v214
	v_exp_f32_e32 v68, v68
	v_cndmask_b32_e32 v82, 0, v82, vcc
	v_cmp_neq_f32_e32 vcc, s30, v64
	v_add_f32_e32 v66, v82, v66
	v_cvt_pk_bf16_f32 v69, v81, v69
	v_cndmask_b32_e32 v83, 0, v67, vcc
	v_cmp_neq_f32_e32 vcc, s30, v65
	v_add_f32_e32 v64, v83, v66
	v_cvt_pk_bf16_f32 v67, v79, v80
	v_cndmask_b32_e32 v84, 0, v68, vcc
	v_add_f32_e32 v102, v84, v64
	v_cvt_pk_bf16_f32 v64, v72, v73
	v_cvt_pk_bf16_f32 v65, v75, v76
	v_cvt_pk_bf16_f32 v66, v77, v78
	v_cvt_pk_bf16_f32 v68, v70, v71
	v_cvt_pk_bf16_f32 v70, v74, v82
	v_cvt_pk_bf16_f32 v71, v83, v84
	s_setprio 1
	v_add_u32_e32 v72, s39, v215
	v_add3_u32 v100, v72, v225, v226
	ds_read_b64_tr_b16 v[72:73], v100 offset:25600
	ds_read_b64_tr_b16 v[74:75], v100 offset:28160
	ds_read_b64_tr_b16 v[76:77], v100 offset:33280
	ds_read_b64_tr_b16 v[78:79], v100 offset:25664
	ds_read_b64_tr_b16 v[82:83], v100 offset:25728
	ds_read_b64_tr_b16 v[86:87], v100 offset:25792
	ds_read_b64_tr_b16 v[80:81], v100 offset:28224
	ds_read_b64_tr_b16 v[84:85], v100 offset:28288
	ds_read_b64_tr_b16 v[88:89], v100 offset:28352
	s_waitcnt lgkmcnt(7)
	v_mfma_f32_32x32x16_bf16 v[48:63], v[72:75], v[64:67], v[48:63]
	ds_read_b64_tr_b16 v[74:75], v100 offset:30720
	ds_read_b64_tr_b16 v[90:91], v100 offset:30784
	ds_read_b64_tr_b16 v[94:95], v100 offset:30848
	ds_read_b64_tr_b16 v[98:99], v100 offset:30912
	ds_read_b64_tr_b16 v[92:93], v100 offset:33344
	ds_read_b64_tr_b16 v[96:97], v100 offset:33408
	ds_read_b64_tr_b16 v[100:101], v100 offset:33472
	s_waitcnt lgkmcnt(9)
	v_mfma_f32_32x32x16_bf16 v[32:47], v[78:81], v[64:67], v[32:47]
	s_waitcnt lgkmcnt(8)
	v_mfma_f32_32x32x16_bf16 v[16:31], v[82:85], v[64:67], v[16:31]
	s_waitcnt lgkmcnt(7)
	v_mfma_f32_32x32x16_bf16 v[0:15], v[86:89], v[64:67], v[0:15]
	v_add_f32_e32 v64, v128, v102
	s_waitcnt lgkmcnt(6)
	v_mfma_f32_32x32x16_bf16 v[48:63], v[74:77], v[68:71], v[48:63]
	s_waitcnt lgkmcnt(2)
	v_mfma_f32_32x32x16_bf16 v[32:47], v[90:93], v[68:71], v[32:47]
	s_waitcnt lgkmcnt(1)
	v_mfma_f32_32x32x16_bf16 v[16:31], v[94:97], v[68:71], v[16:31]
	s_waitcnt lgkmcnt(0)
	v_mfma_f32_32x32x16_bf16 v[0:15], v[98:101], v[68:71], v[0:15]
	s_setprio 0
	v_mov_b32_e32 v65, v64
	s_nop 1
	v_permlane32_swap_b32_e32 v65, v64
	v_lshl_or_b32 v66, s37, 6, v252
	s_cmp_lg_u32 s38, 1
	v_mad_u32_u24 v67, v66, s31, 0
	s_waitcnt lgkmcnt(0)
	v_add_f32_e32 v215, v64, v65
	s_barrier
	s_cbranch_scc1 .LBB0_604
	ds_write2_b64 v67, v[48:49], v[50:51] offset1:1
	ds_write2_b64 v67, v[52:53], v[54:55] offset0:2 offset1:3
	ds_write2_b64 v67, v[56:57], v[58:59] offset0:4 offset1:5
	ds_write2_b64 v67, v[60:61], v[62:63] offset0:6 offset1:7
	ds_write2_b64 v67, v[32:33], v[34:35] offset0:8 offset1:9
	ds_write2_b64 v67, v[36:37], v[38:39] offset0:10 offset1:11
	ds_write2_b64 v67, v[40:41], v[42:43] offset0:12 offset1:13
	ds_write2_b64 v67, v[44:45], v[46:47] offset0:14 offset1:15
	ds_write2_b64 v67, v[16:17], v[18:19] offset0:16 offset1:17
	ds_write2_b64 v67, v[20:21], v[22:23] offset0:18 offset1:19
	ds_write2_b64 v67, v[24:25], v[26:27] offset0:20 offset1:21
	ds_write2_b64 v67, v[28:29], v[30:31] offset0:22 offset1:23
	ds_write2_b64 v67, v[0:1], v[2:3] offset0:24 offset1:25
	ds_write2_b64 v67, v[4:5], v[6:7] offset0:26 offset1:27
	ds_write2_b64 v67, v[8:9], v[10:11] offset0:28 offset1:29
	ds_write2_b64 v67, v[12:13], v[14:15] offset0:30 offset1:31
	ds_write_b64 v67, v[214:215] offset:256

; #define LAS __attribute__((address_space(3)))
; DI float fexp2(float x) { return __builtin_amdgcn_exp2f(x); }
; DI void attn_item(LAS unsigned char* lds, int bh, int qb, const bf16_t* QH, const bf16_t* KN, const bf16_t* KPE, const bf16_t* VT, const bf16_t* P, bf16_t* MIX) {
;     ...
;         { const LAS unsigned char* kp = kb + (kh * 32 + r) * KROW + 16 * h2;
;           __builtin_amdgcn_s_setprio(1);
; #pragma unroll
;           for (int ks = 0; ks < 12; ++ks) { const bf16x8 a = *(const LAS bf16x8*)(kp + 32 * ks); S = __builtin_amdgcn_mfma_f32_32x32x16_bf16(a, Qf[ks], S, 0, 0, 0); }
;           __builtin_amdgcn_sched_group_barrier(0x100, 4, 0);
; #pragma unroll
;           for (int i = 0; i < 8; ++i) { __builtin_amdgcn_sched_group_barrier(0x008, 1, 0); __builtin_amdgcn_sched_group_barrier(0x100, 1, 0); }
;           __builtin_amdgcn_sched_group_barrier(0x008, 4, 0);
;           __builtin_amdgcn_s_setprio(0); }
;         const bool diag = (t >= 2 * qb);
;         if (diag) {
;             const int key0 = t * 64 + kh * 32 + 4 * h2;
; #pragma unroll
;             for (int i = 0; i < 16; ++i) { const int key = key0 + (i & 3) + 8 * (i >> 2); if (key > qpos) S[i] = NEG; }
;         }
;         float mx = S[0];
; #pragma unroll
;         for (int i = 1; i < 16; ++i) mx = fmaxf(mx, S[i]);
;         mx = fmaxf(mx, __shfl_xor(mx, 32));
;         if (__any(mx > mrow + 8.f)) {
;             const float mnew = fmaxf(mrow, mx);
;             const float alpha = fexp2(mrow - mnew);
;             mrow = mnew; lrow *= alpha;
; #pragma unroll
;             for (int d = 0; d < 4; ++d)
; #pragma unroll
;                 for (int i = 0; i < 16; ++i) O[d][i] *= alpha;
;         }
.LBB0_616:
	s_lshl_b32 s18, s18, 6
	s_barrier
	v_add3_u32 v140, s41, v205, v164
	s_setprio 1
	ds_read_b128 v[64:67], v140
	ds_read_b128 v[128:131], v140 offset:32
	ds_read_b128 v[132:135], v140 offset:64
	ds_read_b128 v[136:139], v140 offset:96
	s_waitcnt lgkmcnt(3)
	v_mfma_f32_32x32x16_bf16 v[64:79], v[64:67], v[124:127], 0
	ds_read_b128 v[124:127], v140 offset:128
	s_waitcnt lgkmcnt(3)
	v_mfma_f32_32x32x16_bf16 v[64:79], v[128:131], v[120:123], v[64:79]
	ds_read_b128 v[120:123], v140 offset:160
	s_waitcnt lgkmcnt(3)
	v_mfma_f32_32x32x16_bf16 v[64:79], v[132:135], v[116:119], v[64:79]
	ds_read_b128 v[116:119], v140 offset:192
	s_waitcnt lgkmcnt(3)
	v_mfma_f32_32x32x16_bf16 v[64:79], v[136:139], v[112:115], v[64:79]
	ds_read_b128 v[112:115], v140 offset:224
	s_waitcnt lgkmcnt(3)
	v_mfma_f32_32x32x16_bf16 v[64:79], v[124:127], v[104:107], v[64:79]
	ds_read_b128 v[104:107], v140 offset:256
	s_waitcnt lgkmcnt(3)
	v_mfma_f32_32x32x16_bf16 v[64:79], v[120:123], v[96:99], v[64:79]
	ds_read_b128 v[96:99], v140 offset:288
	s_waitcnt lgkmcnt(3)
	v_mfma_f32_32x32x16_bf16 v[64:79], v[116:119], v[92:95], v[64:79]
	ds_read_b128 v[92:95], v140 offset:320
	s_waitcnt lgkmcnt(3)
	v_mfma_f32_32x32x16_bf16 v[64:79], v[112:115], v[88:91], v[64:79]
	ds_read_b128 v[88:91], v140 offset:352
	s_waitcnt lgkmcnt(3)
	v_mfma_f32_32x32x16_bf16 v[64:79], v[104:107], v[80:83], v[64:79]
	s_waitcnt lgkmcnt(2)
	v_mfma_f32_32x32x16_bf16 v[64:79], v[96:99], v[84:87], v[64:79]
	s_waitcnt lgkmcnt(1)
	v_mfma_f32_32x32x16_bf16 v[64:79], v[92:95], v[108:111], v[64:79]
	s_waitcnt lgkmcnt(0)
	v_mfma_f32_32x32x16_bf16 v[64:79], v[88:91], v[100:103], v[64:79]
	s_setprio 0
	s_addk_i32 s18, 0xff80
	v_add_u32_e32 v88, s18, v204
	v_cmp_le_u32_e32 vcc, v88, v203
	s_nop 7
	v_cndmask_b32_e32 v87, v230, v64, vcc
	v_cmp_lt_u32_e32 vcc, v88, v203
	v_or_b32_e32 v64, 2, v88
	s_nop 0
	v_cndmask_b32_e32 v86, v230, v65, vcc
	v_cmp_le_u32_e32 vcc, v64, v203
	v_or_b32_e32 v64, 3, v88
	v_or_b32_e32 v65, 27, v88
	v_cndmask_b32_e32 v84, v230, v66, vcc
	v_cmp_le_u32_e32 vcc, v64, v203
	v_or_b32_e32 v64, 8, v88
	s_nop 0
	v_cndmask_b32_e32 v85, v230, v67, vcc
	v_cmp_le_u32_e32 vcc, v64, v203
	v_or_b32_e32 v64, 9, v88
	s_nop 0
	v_cndmask_b32_e32 v82, v230, v68, vcc
	v_cmp_le_u32_e32 vcc, v64, v203
	v_or_b32_e32 v64, 10, v88
	s_nop 0
	v_cndmask_b32_e32 v83, v230, v69, vcc
	v_cmp_le_u32_e32 vcc, v64, v203
	v_or_b32_e32 v64, 11, v88
	s_nop 0
	v_cndmask_b32_e32 v80, v230, v70, vcc
	v_cmp_le_u32_e32 vcc, v64, v203
	v_or_b32_e32 v64, 16, v88
	s_nop 0
	v_cndmask_b32_e32 v81, v230, v71, vcc
	v_cmp_le_u32_e32 vcc, v64, v203
	v_or_b32_e32 v64, 17, v88
	s_nop 0
	v_cndmask_b32_e32 v70, v230, v72, vcc
	v_cmp_le_u32_e32 vcc, v64, v203
	v_or_b32_e32 v64, 18, v88
	v_max_f32_e32 v72, v86, v86
	v_cndmask_b32_e32 v71, v230, v73, vcc
	v_max_f32_e32 v73, v87, v87
	v_cmp_le_u32_e32 vcc, v64, v203
	v_or_b32_e32 v64, 19, v88
	v_max_f32_e32 v72, v73, v72
	v_cndmask_b32_e32 v68, v230, v74, vcc
	v_cmp_le_u32_e32 vcc, v64, v203
	v_or_b32_e32 v64, 24, v88
	v_max3_f32 v72, v72, v84, v85
	v_cndmask_b32_e32 v69, v230, v75, vcc
	v_cmp_le_u32_e32 vcc, v64, v203
	v_or_b32_e32 v64, 25, v88
	v_max3_f32 v72, v72, v82, v83
	v_cndmask_b32_e32 v66, v230, v76, vcc
	v_cmp_le_u32_e32 vcc, v64, v203
	v_or_b32_e32 v64, 26, v88
	v_max3_f32 v72, v72, v80, v81
	v_cndmask_b32_e32 v67, v230, v77, vcc
	v_cmp_le_u32_e32 vcc, v64, v203
	v_max3_f32 v72, v72, v70, v71
	v_max3_f32 v72, v72, v68, v69
	v_cndmask_b32_e32 v64, v230, v78, vcc
	v_cmp_le_u32_e32 vcc, v65, v203
	v_max3_f32 v72, v72, v66, v67
	s_nop 0
	v_cndmask_b32_e32 v65, v230, v79, vcc
	v_max3_f32 v72, v72, v64, v65
	v_mov_b32_e32 v73, v72
	s_nop 1
	v_permlane32_swap_b32_e32 v73, v72
	s_waitcnt lgkmcnt(0)
	v_max_f32_e32 v73, v73, v73
	v_max_f32_e32 v72, v72, v73
	v_add_f32_e32 v73, 0x41000000, v200
	v_cmp_gt_f32_e32 vcc, v72, v73
	s_cbranch_vccz .LBB0_618
	v_max_f32_e32 v72, v72, v72
	v_max_f32_e32 v73, v200, v200
	v_max_f32_e32 v73, v73, v72
	v_sub_f32_e32 v72, v200, v73
	v_exp_f32_e32 v72, v72
	v_mov_b32_e32 v200, v73
	v_pk_mul_f32 v[62:63], v[62:63], v[72:73] op_sel_hi:[1,0]
	v_pk_mul_f32 v[60:61], v[60:61], v[72:73] op_sel_hi:[1,0]
	v_pk_mul_f32 v[58:59], v[58:59], v[72:73] op_sel_hi:[1,0]
	v_pk_mul_f32 v[56:57], v[56:57], v[72:73] op_sel_hi:[1,0]
	v_pk_mul_f32 v[54:55], v[54:55], v[72:73] op_sel_hi:[1,0]
	v_pk_mul_f32 v[52:53], v[52:53], v[72:73] op_sel_hi:[1,0]
	v_pk_mul_f32 v[50:51], v[50:51], v[72:73] op_sel_hi:[1,0]
	v_pk_mul_f32 v[48:49], v[48:49], v[72:73] op_sel_hi:[1,0]
	v_pk_mul_f32 v[46:47], v[46:47], v[72:73] op_sel_hi:[1,0]
	v_pk_mul_f32 v[44:45], v[44:45], v[72:73] op_sel_hi:[1,0]
	v_pk_mul_f32 v[42:43], v[42:43], v[72:73] op_sel_hi:[1,0]
	v_pk_mul_f32 v[40:41], v[40:41], v[72:73] op_sel_hi:[1,0]
	v_pk_mul_f32 v[38:39], v[38:39], v[72:73] op_sel_hi:[1,0]
	v_pk_mul_f32 v[36:37], v[36:37], v[72:73] op_sel_hi:[1,0]
	v_pk_mul_f32 v[34:35], v[34:35], v[72:73] op_sel_hi:[1,0]
	v_pk_mul_f32 v[32:33], v[32:33], v[72:73] op_sel_hi:[1,0]
	v_pk_mul_f32 v[30:31], v[30:31], v[72:73] op_sel_hi:[1,0]
	v_pk_mul_f32 v[28:29], v[28:29], v[72:73] op_sel_hi:[1,0]
	v_pk_mul_f32 v[26:27], v[26:27], v[72:73] op_sel_hi:[1,0]
	v_pk_mul_f32 v[24:25], v[24:25], v[72:73] op_sel_hi:[1,0]
	v_pk_mul_f32 v[22:23], v[22:23], v[72:73] op_sel_hi:[1,0]
	v_pk_mul_f32 v[20:21], v[20:21], v[72:73] op_sel_hi:[1,0]
	v_pk_mul_f32 v[18:19], v[18:19], v[72:73] op_sel_hi:[1,0]
	v_pk_mul_f32 v[16:17], v[16:17], v[72:73] op_sel_hi:[1,0]
	v_pk_mul_f32 v[14:15], v[14:15], v[72:73] op_sel_hi:[1,0]
	v_pk_mul_f32 v[12:13], v[12:13], v[72:73] op_sel_hi:[1,0]
	v_pk_mul_f32 v[10:11], v[10:11], v[72:73] op_sel_hi:[1,0]
	v_pk_mul_f32 v[8:9], v[8:9], v[72:73] op_sel_hi:[1,0]
	v_pk_mul_f32 v[6:7], v[6:7], v[72:73] op_sel_hi:[1,0]
	v_pk_mul_f32 v[4:5], v[4:5], v[72:73] op_sel_hi:[1,0]
	v_pk_mul_f32 v[2:3], v[2:3], v[72:73] op_sel_hi:[1,0]
	v_pk_mul_f32 v[0:1], v[0:1], v[72:73] op_sel_hi:[1,0]
	v_mul_f32_e32 v183, v183, v72
; #define LAS __attribute__((address_space(3)))
; DI unsigned pk2(float lo, float hi) { f32x2 v = {lo, hi}; bf2_t b = __builtin_convertvector(v, bf2_t); return __builtin_bit_cast(unsigned, b); }
; DI float fexp2(float x) { return __builtin_amdgcn_exp2f(x); }
; DI void attn_item(LAS unsigned char* lds, int bh, int qb, const bf16_t* QH, const bf16_t* KN, const bf16_t* KPE, const bf16_t* VT, const bf16_t* P, bf16_t* MIX) {
;     ...
;         float ps = 0.f;
; #pragma unroll
;         for (int i = 0; i < 16; ++i) { float p = fexp2(S[i] - mrow); if (diag && S[i] == NEG) p = 0.f; S[i] = p; ps += p; }
;         lrow += ps;
;         bf16x8 pb[2];
; #pragma unroll
;         for (int s2 = 0; s2 < 2; ++s2) { u32x4 w; w.x = pk2(S[8 * s2 + 0], S[8 * s2 + 1]); w.y = pk2(S[8 * s2 + 2], S[8 * s2 + 3]); w.z = pk2(S[8 * s2 + 4], S[8 * s2 + 5]); w.w = pk2(S[8 * s2 + 6], S[8 * s2 + 7]); pb[s2] = __builtin_bit_cast(bf16x8, w); }
;         __builtin_amdgcn_s_setprio(1);
;         {
;             const int li = lane & 15, gd = (lane >> 4) & 1;
;             const LAS unsigned char* vp = vb + (kh * 32 + 4 * h2 + (li >> 2)) * VROW + gd * 32 + (li & 3) * 8;
; #pragma unroll
;             for (int d = 0; d < 4; ++d)
; #pragma unroll
;                 for (int s2 = 0; s2 < 2; ++s2) {
;                     const s16x4 lo = __builtin_amdgcn_ds_read_tr16_b64_v4i16((LAS s16x4*)(vp + (16 * s2) * VROW + 64 * d));
;                     const s16x4 hi = __builtin_amdgcn_ds_read_tr16_b64_v4i16((LAS s16x4*)(vp + (16 * s2 + 8) * VROW + 64 * d));
;                     const bf16x8 av = __builtin_shufflevector(lo, hi, 0, 1, 2, 3, 4, 5, 6, 7);
;                     O[d] = __builtin_amdgcn_mfma_f32_32x32x16_bf16(av, pb[s2], O[d], 0, 0, 0);
;                 }
;         }
;         __builtin_amdgcn_s_setprio(0);
;     }
;     __syncthreads();
;     ...
;     lrow += __shfl_xor(lrow, 32);
;     LAS float* mb = (LAS float*)lds + (rg * 64 + lane) * 66;
;     if (kh == 1) {
; #pragma unroll
;         for (int d = 0; d < 4; ++d)
; #pragma unroll
;             for (int i = 0; i < 16; ++i) mb[d * 16 + i] = O[d][i];
;         mb[64] = mrow; mb[65] = lrow;
.LBB0_618:
	v_sub_f32_e32 v72, v87, v200
	v_exp_f32_e32 v72, v72
	v_sub_f32_e32 v73, v86, v200
	v_exp_f32_e32 v73, v73
	v_sub_f32_e32 v75, v84, v200
	v_exp_f32_e32 v75, v75
	v_sub_f32_e32 v76, v85, v200
	v_cmp_neq_f32_e32 vcc, s30, v87
	v_exp_f32_e32 v76, v76
	v_sub_f32_e32 v77, v82, v200
	v_cndmask_b32_e32 v72, 0, v72, vcc
	v_cmp_neq_f32_e32 vcc, s30, v86
	v_exp_f32_e32 v77, v77
	v_sub_f32_e32 v78, v83, v200
	v_cndmask_b32_e32 v73, 0, v73, vcc
	v_cmp_neq_f32_e32 vcc, s30, v84
	v_exp_f32_e32 v78, v78
	v_sub_f32_e32 v79, v80, v200
	v_cndmask_b32_e32 v75, 0, v75, vcc
	v_cmp_neq_f32_e32 vcc, s30, v85
	v_exp_f32_e32 v79, v79
	v_add_f32_e32 v74, 0, v72
	v_cndmask_b32_e32 v76, 0, v76, vcc
	v_cmp_neq_f32_e32 vcc, s30, v82
	v_sub_f32_e32 v82, v81, v200
	v_exp_f32_e32 v82, v82
	v_cndmask_b32_e32 v77, 0, v77, vcc
	v_cmp_neq_f32_e32 vcc, s30, v83
	v_add_f32_e32 v74, v73, v74
	v_add_f32_e32 v74, v75, v74
	v_cndmask_b32_e32 v78, 0, v78, vcc
	v_cmp_neq_f32_e32 vcc, s30, v80
	v_add_f32_e32 v74, v76, v74
	v_add_f32_e32 v74, v77, v74
	v_cndmask_b32_e32 v79, 0, v79, vcc
	v_cmp_neq_f32_e32 vcc, s30, v81
	v_sub_f32_e32 v81, v70, v200
	v_exp_f32_e32 v81, v81
	v_cndmask_b32_e32 v80, 0, v82, vcc
	v_sub_f32_e32 v82, v71, v200
	v_cmp_neq_f32_e32 vcc, s30, v70
	v_exp_f32_e32 v82, v82
	v_add_f32_e32 v74, v78, v74
	v_cndmask_b32_e32 v70, 0, v81, vcc
	v_sub_f32_e32 v81, v68, v200
	v_exp_f32_e32 v81, v81
	v_add_f32_e32 v74, v79, v74
	v_add_f32_e32 v74, v80, v74
	v_cmp_neq_f32_e32 vcc, s30, v71
	v_add_f32_e32 v74, v70, v74
	s_nop 0
	v_cndmask_b32_e32 v71, 0, v82, vcc
	v_cmp_neq_f32_e32 vcc, s30, v68
	v_add_f32_e32 v74, v71, v74
	v_sub_f32_e32 v82, v69, v200
	v_cndmask_b32_e32 v81, 0, v81, vcc
	v_exp_f32_e32 v82, v82
	v_add_f32_e32 v68, v81, v74
	v_sub_f32_e32 v74, v66, v200
	v_exp_f32_e32 v74, v74
	v_cmp_neq_f32_e32 vcc, s30, v69
	s_nop 1
	v_cndmask_b32_e32 v69, 0, v82, vcc
	v_sub_f32_e32 v82, v67, v200
	v_cmp_neq_f32_e32 vcc, s30, v66
	v_add_f32_e32 v68, v69, v68
	v_exp_f32_e32 v82, v82
	v_cndmask_b32_e32 v74, 0, v74, vcc
	v_cmp_neq_f32_e32 vcc, s30, v67
	v_sub_f32_e32 v67, v64, v200
	v_add_f32_e32 v66, v74, v68
	v_exp_f32_e32 v67, v67
	v_sub_f32_e32 v68, v65, v200
	v_exp_f32_e32 v68, v68
	v_cndmask_b32_e32 v82, 0, v82, vcc
	v_cmp_neq_f32_e32 vcc, s30, v64
	v_add_f32_e32 v66, v82, v66
	v_cvt_pk_bf16_f32 v69, v81, v69
	v_cndmask_b32_e32 v83, 0, v67, vcc
	v_cmp_neq_f32_e32 vcc, s30, v65
	v_add_f32_e32 v64, v83, v66
	v_cvt_pk_bf16_f32 v67, v79, v80
	v_cndmask_b32_e32 v84, 0, v68, vcc
	v_add_f32_e32 v102, v84, v64
	v_cvt_pk_bf16_f32 v64, v72, v73
	v_cvt_pk_bf16_f32 v65, v75, v76
	v_cvt_pk_bf16_f32 v66, v77, v78
	v_cvt_pk_bf16_f32 v68, v70, v71
	v_cvt_pk_bf16_f32 v70, v74, v82
	v_cvt_pk_bf16_f32 v71, v83, v84
	s_setprio 1
	v_add_u32_e32 v72, s41, v201
	v_add3_u32 v100, v72, v225, v226
	ds_read_b64_tr_b16 v[72:73], v100 offset:25600
	ds_read_b64_tr_b16 v[74:75], v100 offset:28160
	ds_read_b64_tr_b16 v[76:77], v100 offset:33280
	ds_read_b64_tr_b16 v[78:79], v100 offset:25664
	ds_read_b64_tr_b16 v[82:83], v100 offset:25728
	ds_read_b64_tr_b16 v[86:87], v100 offset:25792
	ds_read_b64_tr_b16 v[80:81], v100 offset:28224
	ds_read_b64_tr_b16 v[84:85], v100 offset:28288
	ds_read_b64_tr_b16 v[88:89], v100 offset:28352
	s_waitcnt lgkmcnt(7)
	v_mfma_f32_32x32x16_bf16 v[48:63], v[72:75], v[64:67], v[48:63]
	ds_read_b64_tr_b16 v[74:75], v100 offset:30720
	ds_read_b64_tr_b16 v[90:91], v100 offset:30784
	ds_read_b64_tr_b16 v[94:95], v100 offset:30848
	ds_read_b64_tr_b16 v[98:99], v100 offset:30912
	ds_read_b64_tr_b16 v[92:93], v100 offset:33344
	ds_read_b64_tr_b16 v[96:97], v100 offset:33408
	ds_read_b64_tr_b16 v[100:101], v100 offset:33472
	s_waitcnt lgkmcnt(9)
	v_mfma_f32_32x32x16_bf16 v[32:47], v[78:81], v[64:67], v[32:47]
	s_waitcnt lgkmcnt(8)
	v_mfma_f32_32x32x16_bf16 v[16:31], v[82:85], v[64:67], v[16:31]
	s_waitcnt lgkmcnt(7)
	v_mfma_f32_32x32x16_bf16 v[0:15], v[86:89], v[64:67], v[0:15]
	v_add_f32_e32 v64, v183, v102
	s_waitcnt lgkmcnt(6)
	v_mfma_f32_32x32x16_bf16 v[48:63], v[74:77], v[68:71], v[48:63]
	s_waitcnt lgkmcnt(2)
	v_mfma_f32_32x32x16_bf16 v[32:47], v[90:93], v[68:71], v[32:47]
	s_waitcnt lgkmcnt(1)
	v_mfma_f32_32x32x16_bf16 v[16:31], v[94:97], v[68:71], v[16:31]
	s_waitcnt lgkmcnt(0)
	v_mfma_f32_32x32x16_bf16 v[0:15], v[98:101], v[68:71], v[0:15]
	s_setprio 0
	v_mov_b32_e32 v65, v64
	s_nop 1
	v_permlane32_swap_b32_e32 v65, v64
	v_lshl_or_b32 v66, s39, 6, v252
	s_cmp_lg_u32 s40, 1
	v_mad_u32_u24 v67, v66, s31, 0
	s_waitcnt lgkmcnt(0)
	v_add_f32_e32 v201, v64, v65
	s_barrier
	s_cbranch_scc1 .LBB0_620
	ds_write2_b64 v67, v[48:49], v[50:51] offset1:1
	ds_write2_b64 v67, v[52:53], v[54:55] offset0:2 offset1:3
	ds_write2_b64 v67, v[56:57], v[58:59] offset0:4 offset1:5
	ds_write2_b64 v67, v[60:61], v[62:63] offset0:6 offset1:7
	ds_write2_b64 v67, v[32:33], v[34:35] offset0:8 offset1:9
	ds_write2_b64 v67, v[36:37], v[38:39] offset0:10 offset1:11
	ds_write2_b64 v67, v[40:41], v[42:43] offset0:12 offset1:13
	ds_write2_b64 v67, v[44:45], v[46:47] offset0:14 offset1:15
	ds_write2_b64 v67, v[16:17], v[18:19] offset0:16 offset1:17
	ds_write2_b64 v67, v[20:21], v[22:23] offset0:18 offset1:19
	ds_write2_b64 v67, v[24:25], v[26:27] offset0:20 offset1:21
	ds_write2_b64 v67, v[28:29], v[30:31] offset0:22 offset1:23
	ds_write2_b64 v67, v[0:1], v[2:3] offset0:24 offset1:25
	ds_write2_b64 v67, v[4:5], v[6:7] offset0:26 offset1:27
	ds_write2_b64 v67, v[8:9], v[10:11] offset0:28 offset1:29
	ds_write2_b64 v67, v[12:13], v[14:15] offset0:30 offset1:31
	ds_write_b64 v67, v[200:201] offset:256

; DI void hgC_item(LAS unsigned char* lds, unsigned char* ws, unsigned char* ob, int item, const float* ng, int dummy, const unsigned (&lfr)[16], const unsigned (&qvr)[16], const u32x4 (&ivw)[2], const float* lbp) {
;     ...
;     float ss = 0.f;
; #pragma unroll
;     for (int i = 0; i < 16; ++i) ss += acc[i] * acc[i];
;     ss += __shfl_xor(ss, 32);
;     if (h2 == 0) red[vb * 64 + tb * 32 + r] = ss;
.LBB0_1122:
	s_nop 11
	v_mul_f32_e32 v16, v1, v1
	v_fmac_f32_e32 v16, v0, v0
	v_fmac_f32_e32 v16, v2, v2
	v_fmac_f32_e32 v16, v3, v3
	v_fmac_f32_e32 v16, v4, v4
	v_fmac_f32_e32 v16, v5, v5
	v_fmac_f32_e32 v16, v6, v6
	v_fmac_f32_e32 v16, v7, v7
	v_fmac_f32_e32 v16, v8, v8
	v_fmac_f32_e32 v16, v9, v9
	v_fmac_f32_e32 v16, v10, v10
	v_fmac_f32_e32 v16, v11, v11
	v_fmac_f32_e32 v16, v12, v12
	v_fmac_f32_e32 v16, v13, v13
	v_fmac_f32_e32 v16, v14, v14
	v_fmac_f32_e32 v16, v15, v15
	v_mov_b32_e32 v17, v16
	s_nop 1
	v_permlane32_swap_b32_e32 v17, v16
	s_lshl_b32 s97, s91, 7
	s_and_saveexec_b64 s[90:91], s[54:55]
	s_cbranch_execz .LBB0_1111
	s_lshl_b32 s33, s75, 8
	s_add_i32 s33, s33, 0
	s_lshl_b32 s56, s68, 2
	s_add_i32 s33, s33, s56
	s_waitcnt lgkmcnt(0)
	v_add_f32_e32 v16, v16, v17
	v_lshl_add_u32 v17, v100, 2, s33
	v_add_u32_e32 v17, 0x12400, v17
	ds_write_b32 v17, v16
	s_branch .LBB0_1111
